# ps1 + static s_setprio 2 for the four compute waves of the sample diff unit (loader waves stay at 0)
# baseline (speedup 1.0000x reference)
;     ...
;         const int qrow = NP + b * 64 + 32 * qblk + r32, qpos = PAST + 32 * qblk + r32;
;         const float c15 = tab[0];
;         const lcp qp0 = (lcp)(lds + S2_Q) + wid * 4096 + lane * 16;
;         {
;             bf16x8 qr[4]; const bf16* qsrc = C.DQ + (size_t)qrow * 512 + h * 128 + map * 64;
; #pragma unroll
;             for (int d0 = 0; d0 < 4; ++d0) qr[d0] = *(const bf16x8*)(qsrc + d0 * 16 + hi * 8);
; #pragma unroll
;             for (int d0 = 0; d0 < 4; ++d0) *(LAS bf16x8*)((LAS unsigned char*)qp0 + d0 * 1024) = qr[d0];
;         }
;     ...
;         unsigned ka0, ka1, ka2, ka3;
;         { const int c0 = hi, c1 = 2 + hi, c2 = 4 + hi, c3 = 6 + hi;
;           ka0 = map * 8192 + c0 * 1024 + ((r32 ^ c0) & 63) * 16; ka1 = map * 8192 + c1 * 1024 + ((r32 ^ c1) & 63) * 16;
;           ka2 = map * 8192 + c2 * 1024 + ((r32 ^ c2) & 63) * 16; ka3 = map * 8192 + c3 * 1024 + ((r32 ^ c3) & 63) * 16; }
;         const lcp vp0 = (lcp)(lds + S2_V) + ((lane >> 4) & 1) * 32 + (lane & 3) * 8 + (4 * hi + ((lane & 15) >> 2)) * 64;
;         bf16x8 kf[8];
;         float nm = c15;
; #pragma unroll
;         for (int d = 0; d < 4; ++d) o[d] = (f32x16){0.f,0.f,0.f,0.f,0.f,0.f,0.f,0.f,0.f,0.f,0.f,0.f,0.f,0.f,0.f,0.f};
;         bool resc = false;
;     ...
;         f32x16 pA0, pA1, pB0, pB1;
;         S2BAR();
;         {
;             INITC(pA0, pA1);
;             { const bf16x8 b0 = *(const LAS bf16x8*)(lds + ka0), b1 = *(const LAS bf16x8*)(lds + ka0 + 512); const bf16x8 qv = QRD(0);
;               pA0 = __builtin_amdgcn_mfma_f32_32x32x16_bf16(b0, qv, pA0, 0, 0, 0); pA1 = __builtin_amdgcn_mfma_f32_32x32x16_bf16(b1, qv, pA1, 0, 0, 0); }
;             { const bf16x8 b0 = *(const LAS bf16x8*)(lds + ka1), b1 = *(const LAS bf16x8*)(lds + ka1 + 512); const bf16x8 qv = QRD(1);
;               pA0 = __builtin_amdgcn_mfma_f32_32x32x16_bf16(b0, qv, pA0, 0, 0, 0); pA1 = __builtin_amdgcn_mfma_f32_32x32x16_bf16(b1, qv, pA1, 0, 0, 0); }
;             { const bf16x8 b0 = *(const LAS bf16x8*)(lds + ka2), b1 = *(const LAS bf16x8*)(lds + ka2 + 512); const bf16x8 qv = QRD(2);
;               pA0 = __builtin_amdgcn_mfma_f32_32x32x16_bf16(b0, qv, pA0, 0, 0, 0); pA1 = __builtin_amdgcn_mfma_f32_32x32x16_bf16(b1, qv, pA1, 0, 0, 0); }
;             { const bf16x8 b0 = *(const LAS bf16x8*)(lds + ka3), b1 = *(const LAS bf16x8*)(lds + ka3 + 512); const bf16x8 qv = QRD(3);
.LBB0_304:
	s_bfe_u32 s61, s5, 0x10007
	s_and_b32 s5, s5, 0x3fffffc0
	s_lshl_b32 s5, s5, 2
	s_add_i32 s62, s5, 0
	v_bfe_u32 v209, v140, 5, 1
	s_and_b32 s60, s4, 1
	s_add_i32 s62, s62, 0x21c00
	s_and_b64 vcc, exec, s[2:3]
	v_lshlrev_b32_e32 v200, 8, v142
	s_cbranch_vccz .LBB0_348
	s_setprio 2
	v_lshlrev_b32_e32 v2, 6, v207
	s_lshl_b32 s14, s60, 5
	v_or_b32_e32 v2, s14, v2
	v_or_b32_e32 v2, v2, v208
	v_readlane_b32 s2, v253, 54
	v_lshlrev_b32_e32 v2, 10, v2
	v_mov_b32_e32 v3, v201
	v_readlane_b32 s3, v253, 55
	s_lshl_b32 s6, s61, 7
	v_lshlrev_b32_e32 v202, 4, v209
	v_lshl_add_u64 v[2:3], s[2:3], 0, v[2:3]
	v_lshl_add_u64 v[2:3], v[2:3], 0, v[200:201]
	v_lshl_add_u64 v[2:3], v[2:3], 0, s[6:7]
	v_mov_b32_e32 v203, v201
	v_lshl_add_u64 v[2:3], v[2:3], 0, v[202:203]
	s_mov_b64 s[2:3], 0x1000000
	v_lshl_add_u64 v[14:15], v[2:3], 0, s[2:3]
	s_mov_b32 s2, 0x1000000
	v_add_co_u32_e32 v2, vcc, s2, v2
	s_movk_i32 s2, 0x300
	s_nop 0
	v_addc_co_u32_e32 v3, vcc, 0, v3, vcc
	global_load_dwordx4 v[2:5], v[2:3], off
	s_nop 0
	global_load_dwordx4 v[6:9], v[14:15], off offset:32
	global_load_dwordx4 v[10:13], v[14:15], off offset:64
	s_nop 0
	global_load_dwordx4 v[14:17], v[14:15], off offset:96
	v_mul_lo_u32 v18, v142, s2
	s_lshl_b32 s2, s4, 12
	v_and_b32_e32 v50, 63, v140
	s_add_i32 s2, s2, 0
	v_add_u32_e32 v18, 0, v18
	v_lshlrev_b32_e32 v21, 4, v50
	s_add_i32 s2, s2, 0x22800
	v_xor_b32_e32 v19, v209, v208
	v_add_u32_e32 v210, 0x20400, v18
	v_add_u32_e32 v212, s2, v21
	s_lshl_b32 s3, s61, 13
	v_lshl_add_u32 v20, v209, 10, 0
	ds_read_b32 v66, v210
	v_lshlrev_b32_e32 v18, 4, v19
	v_add3_u32 v211, v20, v18, s3
	v_mov_b32_e32 v51, v201
	v_mov_b32_e32 v52, v201
	s_waitcnt lgkmcnt(0)
	v_mov_b32_e32 v67, v66
	v_mov_b32_e32 v68, v66
	v_mov_b32_e32 v69, v66
	v_mov_b32_e32 v70, v66
	v_mov_b32_e32 v71, v66
	v_mov_b32_e32 v72, v66
	v_mov_b32_e32 v73, v66
	v_mov_b32_e32 v74, v66
	v_mov_b32_e32 v75, v66
	v_mov_b32_e32 v76, v66
	v_mov_b32_e32 v77, v66
	v_mov_b32_e32 v78, v66
	v_mov_b32_e32 v79, v66
	v_mov_b32_e32 v80, v66
	v_mov_b32_e32 v81, v66
	v_mov_b32_e32 v53, v201
	v_mov_b32_e32 v54, v201
	v_mov_b32_e32 v55, v201
	v_mov_b32_e32 v56, v201
	v_mov_b32_e32 v57, v201
	v_mov_b32_e32 v58, v201
	v_mov_b32_e32 v59, v201
	v_mov_b32_e32 v60, v201
	v_mov_b32_e32 v61, v201
	v_mov_b32_e32 v62, v201
	v_mov_b32_e32 v63, v201
	v_mov_b32_e32 v64, v201
	v_mov_b32_e32 v65, v201
	v_mov_b32_e32 v219, 0
	s_mov_b32 s6, -1
	s_mov_b32 s15, 0x20000
	s_waitcnt vmcnt(3)
	ds_write_b128 v212, v[2:5]
	s_waitcnt vmcnt(2)
	ds_write_b128 v212, v[6:9] offset:1024
	s_waitcnt vmcnt(1)
	ds_write_b128 v212, v[10:13] offset:2048
	s_waitcnt vmcnt(0)
	ds_write_b128 v212, v[14:17] offset:3072
	s_waitcnt lgkmcnt(0)
	s_barrier
	ds_read_b128 v[18:21], v211
	ds_read_b128 v[34:37], v212
	ds_read_b128 v[38:41], v211 offset:512
	ds_read_b128 v[42:45], v212 offset:1024
	s_waitcnt lgkmcnt(2)
	v_mfma_f32_32x32x16_bf16 v[2:17], v[18:21], v[34:37], v[66:81]
	v_or_b32_e32 v18, 2, v209
	v_bitop3_b32 v19, v209, v208, 2 bitop3:0x36
	v_lshlrev_b32_e32 v18, 10, v18
	v_lshl_add_u32 v19, v19, 4, 0
	v_add3_u32 v213, v19, v18, s3
	v_mov_b64_e32 v[18:19], v[66:67]
	v_mov_b64_e32 v[20:21], v[68:69]
	v_mov_b64_e32 v[22:23], v[70:71]
	v_mov_b64_e32 v[24:25], v[72:73]
	v_mov_b64_e32 v[26:27], v[74:75]
	v_mov_b64_e32 v[28:29], v[76:77]
	v_mov_b64_e32 v[30:31], v[78:79]
	v_mov_b64_e32 v[32:33], v[80:81]
	v_lshl_add_u32 v67, v208, 2, s62
	s_waitcnt lgkmcnt(1)
	v_mfma_f32_32x32x16_bf16 v[18:33], v[38:41], v[34:37], v[18:33]
	ds_read_b128 v[34:37], v213
	ds_read_b128 v[38:41], v213 offset:512
	s_waitcnt lgkmcnt(1)
	v_mfma_f32_32x32x16_bf16 v[2:17], v[34:37], v[42:45], v[2:17]
	v_or_b32_e32 v34, 4, v209
	v_bitop3_b32 v35, v209, v208, 4 bitop3:0x36
	v_lshlrev_b32_e32 v34, 10, v34
	v_lshl_add_u32 v35, v35, 4, 0
	v_add3_u32 v214, v35, v34, s3
	s_waitcnt lgkmcnt(0)
	v_mfma_f32_32x32x16_bf16 v[18:33], v[38:41], v[42:45], v[18:33]
	ds_read_b128 v[34:37], v214
	ds_read_b128 v[38:41], v212 offset:2048
	ds_read_b128 v[42:45], v214 offset:512
	ds_read_b128 v[46:49], v212 offset:3072
	s_waitcnt lgkmcnt(2)
	v_mfma_f32_32x32x16_bf16 v[2:17], v[34:37], v[38:41], v[2:17]
	v_or_b32_e32 v34, 6, v209
	v_bitop3_b32 v35, v209, v208, 6 bitop3:0x36
	v_lshlrev_b32_e32 v34, 10, v34
	v_lshl_add_u32 v35, v35, 4, 0
	v_add3_u32 v215, v35, v34, s3
	v_cmp_gt_u32_e64 s[2:3], 32, v50
	v_mov_b32_e32 v50, v201
	s_waitcnt lgkmcnt(1)
	v_mfma_f32_32x32x16_bf16 v[18:33], v[42:45], v[38:41], v[18:33]
	ds_read_b128 v[34:37], v215
	ds_read_b128 v[38:41], v215 offset:512
	ds_read_b128 v[192:195], v211 offset:32768
	ds_read_b128 v[184:187], v211 offset:33280
	ds_read_b128 v[188:191], v213 offset:32768
	ds_read_b128 v[180:183], v213 offset:33280
	ds_read_b128 v[176:179], v214 offset:32768
	ds_read_b128 v[172:175], v214 offset:33280
	ds_read_b128 v[168:171], v215 offset:32768
	ds_read_b128 v[164:167], v215 offset:33280
	s_waitcnt lgkmcnt(0)
	s_barrier
; #define TMX3(a, b, c) __builtin_fmaxf(__builtin_fmaxf((a), (b)), (c))
; #define TEX(v) __builtin_amdgcn_exp2f(v)
; #define S2BAR() asm volatile("s_waitcnt lgkmcnt(0)\n\ts_barrier" ::: "memory")
; #define KLD(j, KA, soff) do { kf[2 * (j)] = *(const LAS bf16x8*)(lds + (KA) + (soff)); kf[2 * (j) + 1] = *(const LAS bf16x8*)(lds + (KA) + (soff) + 512); } while (0)
;     ...
;             float rm = TMX3(pA0[0], pA0[1], pA1[0]);
; #pragma unroll
;             for (int r = 1; r < 16; ++r) rm = TMX3(rm, pA0[r], pA1[r]);
;             { auto rr = __builtin_amdgcn_permlane32_swap(__float_as_uint(rm), __float_as_uint(rm), false, false); rm = __builtin_fmaxf(__uint_as_float(rr[0]), __uint_as_float(rr[1])); }
;             nm -= rm;
; #pragma unroll
;             for (int r = 0; r < 16; ++r) { pA0[r] = TEX(pA0[r] - rm); pA1[r] = TEX(pA1[r] - rm); }
;         }
;         KLD(0, ka0, S2_SLOT); KLD(1, ka1, S2_SLOT); KLD(2, ka2, S2_SLOT); KLD(3, ka3, S2_SLOT);
;         S2BAR();
;         s16x4 vl0, vh0, vl1, vh1, vl2, vh2, vl3, vh3; v4u pw0, pw1, pw2, pw3;
;         bf16x8 qa = QRD(0), qb_;
	ds_read_b128 v[196:199], v212
	s_waitcnt lgkmcnt(10)
	v_mfma_f32_32x32x16_bf16 v[2:17], v[34:37], v[46:49], v[2:17]
	v_lshlrev_b32_e32 v34, 1, v140
	v_and_b32_e32 v35, 24, v141
	v_and_b32_e32 v34, 32, v34
	v_add3_u32 v34, 0, v34, v35
	v_lshlrev_b32_e32 v37, 4, v140
	v_lshlrev_b32_e32 v36, 8, v209
	v_and_b32_e32 v37, 0xc0, v37
	s_waitcnt lgkmcnt(9)
	v_mfma_f32_32x32x16_bf16 v[18:33], v[38:41], v[46:49], v[18:33]
	v_add3_u32 v203, v34, v36, v37
	s_nop 10
	v_max3_f32 v35, v2, v3, v18
	v_max3_f32 v35, v35, v3, v19
	v_max3_f32 v35, v35, v4, v20
	v_max3_f32 v35, v35, v5, v21
	v_max3_f32 v35, v35, v6, v22
	v_max3_f32 v35, v35, v7, v23
	v_max3_f32 v35, v35, v8, v24
	v_max3_f32 v35, v35, v9, v25
	v_max3_f32 v35, v35, v10, v26
	v_max3_f32 v35, v35, v11, v27
	v_max3_f32 v35, v35, v12, v28
	v_max3_f32 v35, v35, v13, v29
	v_max3_f32 v35, v35, v14, v30
	v_max3_f32 v35, v35, v15, v31
	v_max3_f32 v35, v35, v16, v32
	v_max3_f32 v35, v35, v17, v33
	v_mov_b32_e32 v38, v35
	s_nop 1
	v_permlane32_swap_b32_e32 v35, v38
	v_max_f32_e32 v38, v38, v38
	v_max_f32_e32 v35, v35, v35
	v_max_f32_e32 v35, v35, v38
	v_sub_f32_e32 v2, v2, v35
	v_exp_f32_e32 v100, v2
	v_sub_f32_e32 v2, v10, v35
	v_exp_f32_e32 v108, v2
	v_sub_f32_e32 v2, v26, v35
	v_exp_f32_e32 v92, v2
	v_sub_f32_e32 v2, v11, v35
	v_exp_f32_e32 v109, v2
	v_sub_f32_e32 v2, v27, v35
	v_exp_f32_e32 v93, v2
	v_sub_f32_e32 v2, v12, v35
	v_exp_f32_e32 v110, v2
	v_sub_f32_e32 v2, v28, v35
	v_exp_f32_e32 v94, v2
	v_sub_f32_e32 v2, v13, v35
	v_exp_f32_e32 v111, v2
	v_sub_f32_e32 v2, v29, v35
	v_exp_f32_e32 v95, v2
	v_sub_f32_e32 v2, v14, v35
	v_exp_f32_e32 v112, v2
	v_sub_f32_e32 v2, v30, v35
	v_exp_f32_e32 v96, v2
	v_sub_f32_e32 v2, v15, v35
	v_exp_f32_e32 v113, v2
	v_sub_f32_e32 v2, v31, v35
	v_exp_f32_e32 v97, v2
	v_sub_f32_e32 v2, v16, v35
	v_exp_f32_e32 v114, v2
	v_sub_f32_e32 v2, v32, v35
	v_exp_f32_e32 v98, v2
	v_sub_f32_e32 v2, v17, v35
	v_sub_f32_e32 v18, v18, v35
	v_sub_f32_e32 v3, v3, v35
	v_sub_f32_e32 v19, v19, v35
	v_sub_f32_e32 v4, v4, v35
	v_sub_f32_e32 v20, v20, v35
	v_sub_f32_e32 v5, v5, v35
	v_sub_f32_e32 v21, v21, v35
	v_sub_f32_e32 v6, v6, v35
	v_sub_f32_e32 v22, v22, v35
	v_sub_f32_e32 v7, v7, v35
	v_sub_f32_e32 v23, v23, v35
	v_sub_f32_e32 v8, v8, v35
	v_sub_f32_e32 v24, v24, v35
	v_sub_f32_e32 v9, v9, v35
	v_sub_f32_e32 v25, v25, v35
	v_exp_f32_e32 v115, v2
	v_sub_f32_e32 v2, v33, v35
	v_exp_f32_e32 v84, v18
	v_exp_f32_e32 v101, v3
	v_exp_f32_e32 v85, v19
	v_exp_f32_e32 v102, v4
	v_exp_f32_e32 v86, v20
	v_exp_f32_e32 v103, v5
	v_exp_f32_e32 v87, v21
	v_exp_f32_e32 v104, v6
	v_exp_f32_e32 v88, v22
	v_exp_f32_e32 v105, v7
	v_exp_f32_e32 v89, v23
	v_exp_f32_e32 v106, v8
	v_exp_f32_e32 v90, v24
	v_exp_f32_e32 v107, v9
	v_exp_f32_e32 v91, v25
	v_exp_f32_e32 v99, v2
	v_sub_f32_e32 v68, v66, v35
	v_mov_b64_e32 v[34:35], v[50:51]
	v_mov_b64_e32 v[18:19], v[50:51]
	v_mov_b64_e32 v[2:3], v[50:51]
	v_mov_b64_e32 v[36:37], v[52:53]
	v_mov_b64_e32 v[38:39], v[54:55]
	v_mov_b64_e32 v[40:41], v[56:57]
	v_mov_b64_e32 v[42:43], v[58:59]
	v_mov_b64_e32 v[44:45], v[60:61]
	v_mov_b64_e32 v[46:47], v[62:63]
	v_mov_b64_e32 v[48:49], v[64:65]
	v_mov_b64_e32 v[20:21], v[52:53]
	v_mov_b64_e32 v[22:23], v[54:55]
	v_mov_b64_e32 v[24:25], v[56:57]
	v_mov_b64_e32 v[26:27], v[58:59]
	v_mov_b64_e32 v[28:29], v[60:61]
	v_mov_b64_e32 v[30:31], v[62:63]
	v_mov_b64_e32 v[32:33], v[64:65]
	v_mov_b64_e32 v[4:5], v[52:53]
	v_mov_b64_e32 v[6:7], v[54:55]
	v_mov_b64_e32 v[8:9], v[56:57]
	v_mov_b64_e32 v[10:11], v[58:59]
	v_mov_b64_e32 v[12:13], v[60:61]
	v_mov_b64_e32 v[14:15], v[62:63]
	v_mov_b64_e32 v[16:17], v[64:65]
	s_branch .LBB0_307

; #define LAS __attribute__((address_space(3)))
; __device__ __forceinline__ int crow(int r, int hi) { return (r & 3) + 8 * (r >> 2) + 4 * hi; }
;     ...
;     __syncthreads();
;     if (DRY) { if (DRY == 2 && wid < 4) { float sink_ = l_reg + o[0][0] + o[1][1] + o[2][2] + o[3][3]; asm volatile("" :: "v"(sink_)); } return; }
;     if (wid < 4) {
;         LAS float* F = (LAS float*)lds + (size_t)(map * 64 + 32 * qblk) * 128;
; #pragma unroll
;         for (int gq = 0; gq < 4; ++gq) { const f32x4 a = *(const LAS f32x4*)(wsf + 8 * gq + 4 * hi);
; #pragma unroll
;             for (int d = 0; d < 4; ++d)
; #pragma unroll
;                 for (int e = 0; e < 4; ++e) { const int r = 4 * gq + e; F[crow(r, hi) * 128 + 32 * d + r32] = o[d][r] * a[e]; } }
;     }
.LBB0_348:
	s_setprio 0
	s_andn2_b64 vcc, exec, s[10:11]
	s_waitcnt lgkmcnt(0)
	s_barrier
	s_cbranch_vccnz .LBB0_350
	v_lshl_add_u32 v70, v209, 4, s62
	ds_read_b128 v[66:69], v70
	s_lshl_b32 s2, s61, 15
	s_add_i32 s2, s2, 0
	s_lshl_b32 s3, s60, 14
	s_add_i32 s2, s2, s3
	v_lshlrev_b32_e32 v71, 11, v209
	v_lshlrev_b32_e32 v72, 2, v208
	s_waitcnt lgkmcnt(0)
	v_mul_f32_e32 v50, v50, v66
	v_add3_u32 v71, s2, v72, v71
	v_mul_f32_e32 v34, v34, v66
	v_mul_f32_e32 v18, v18, v66
	v_mul_f32_e32 v2, v2, v66
	v_mul_f32_e32 v51, v51, v67
	ds_write2_b32 v71, v50, v34 offset1:32
	v_mul_f32_e32 v34, v35, v67
	v_mul_f32_e32 v19, v19, v67
	ds_write2_b32 v71, v18, v2 offset0:64 offset1:96
	v_mul_f32_e32 v2, v3, v67
	v_mul_f32_e32 v52, v52, v68
	ds_write2_b32 v71, v51, v34 offset0:128 offset1:160
	v_mul_f32_e32 v34, v36, v68
	v_add_u32_e32 v35, 0x400, v71
	v_mul_f32_e32 v20, v20, v68
	ds_write2_b32 v71, v19, v2 offset0:192 offset1:224
	v_mul_f32_e32 v2, v4, v68
	v_mul_f32_e32 v53, v53, v69
	ds_write2_b32 v35, v52, v34 offset1:32
	v_mul_f32_e32 v34, v37, v69
	v_mul_f32_e32 v21, v21, v69
	ds_write2_b32 v35, v20, v2 offset0:64 offset1:96
	v_mul_f32_e32 v2, v5, v69
	ds_write2_b32 v35, v53, v34 offset0:128 offset1:160
	ds_write2_b32 v35, v21, v2 offset0:192 offset1:224
	ds_read_b128 v[2:5], v70 offset:32
	v_add_u32_e32 v35, 0x1000, v71
	s_waitcnt lgkmcnt(0)
	v_mul_f32_e32 v18, v54, v2
	v_mul_f32_e32 v34, v38, v2
	v_mul_f32_e32 v19, v55, v3
	ds_write2_b32 v35, v18, v34 offset1:32
	v_mul_f32_e32 v18, v39, v3
	v_mul_f32_e32 v20, v56, v4
	ds_write2_b32 v35, v19, v18 offset0:128 offset1:160
	v_mul_f32_e32 v18, v40, v4
	v_add_u32_e32 v19, 0x1400, v71
	v_mul_f32_e32 v21, v57, v5
	ds_write2_b32 v19, v20, v18 offset1:32
	v_mul_f32_e32 v18, v41, v5
	ds_write2_b32 v19, v21, v18 offset0:128 offset1:160
	v_mul_f32_e32 v18, v22, v2
	v_mul_f32_e32 v2, v6, v2
	v_mul_f32_e32 v20, v23, v3
	ds_write2_b32 v35, v18, v2 offset0:64 offset1:96
	v_mul_f32_e32 v2, v7, v3
	v_mul_f32_e32 v21, v24, v4
	ds_write2_b32 v35, v20, v2 offset0:192 offset1:224
	v_mul_f32_e32 v2, v8, v4
	v_mul_f32_e32 v22, v25, v5
	ds_write2_b32 v19, v21, v2 offset0:64 offset1:96
	v_mul_f32_e32 v2, v9, v5
	ds_write2_b32 v19, v22, v2 offset0:192 offset1:224
	ds_read_b128 v[2:5], v70 offset:64
	v_add_u32_e32 v19, 0x2000, v71
	s_waitcnt lgkmcnt(0)
	v_mul_f32_e32 v6, v58, v2
	v_mul_f32_e32 v18, v42, v2
	v_mul_f32_e32 v7, v59, v3
	ds_write2_b32 v19, v6, v18 offset1:32
	v_mul_f32_e32 v6, v43, v3
	v_mul_f32_e32 v8, v60, v4
	ds_write2_b32 v19, v7, v6 offset0:128 offset1:160
	v_mul_f32_e32 v6, v44, v4
	v_add_u32_e32 v7, 0x2400, v71
	v_mul_f32_e32 v9, v61, v5
	ds_write2_b32 v7, v8, v6 offset1:32
	v_mul_f32_e32 v6, v45, v5
	ds_write2_b32 v7, v9, v6 offset0:128 offset1:160
	v_mul_f32_e32 v6, v26, v2
	v_mul_f32_e32 v2, v10, v2
	v_mul_f32_e32 v8, v27, v3
	ds_write2_b32 v19, v6, v2 offset0:64 offset1:96
	v_mul_f32_e32 v2, v11, v3
	v_mul_f32_e32 v9, v28, v4
	ds_write2_b32 v19, v8, v2 offset0:192 offset1:224
	v_mul_f32_e32 v2, v12, v4
	v_mul_f32_e32 v18, v29, v5
	ds_write2_b32 v7, v9, v2 offset0:64 offset1:96
	v_mul_f32_e32 v2, v13, v5
	ds_write2_b32 v7, v18, v2 offset0:192 offset1:224
	ds_read_b128 v[2:5], v70 offset:96
	v_add_u32_e32 v11, 0x3000, v71
	s_waitcnt lgkmcnt(0)
	v_mul_f32_e32 v6, v62, v2
	v_mul_f32_e32 v10, v46, v2
	v_mul_f32_e32 v7, v63, v3
	ds_write2_b32 v11, v6, v10 offset1:32
	v_mul_f32_e32 v6, v47, v3
	v_mul_f32_e32 v8, v64, v4
	ds_write2_b32 v11, v7, v6 offset0:128 offset1:160
	v_mul_f32_e32 v6, v48, v4
	v_add_u32_e32 v7, 0x3400, v71
	v_mul_f32_e32 v9, v65, v5
	ds_write2_b32 v7, v8, v6 offset1:32
	v_mul_f32_e32 v6, v49, v5
	ds_write2_b32 v7, v9, v6 offset0:128 offset1:160
	v_mul_f32_e32 v6, v30, v2
	v_mul_f32_e32 v2, v14, v2
	v_mul_f32_e32 v8, v31, v3
	ds_write2_b32 v11, v6, v2 offset0:64 offset1:96
	v_mul_f32_e32 v2, v15, v3
	v_mul_f32_e32 v9, v32, v4
	ds_write2_b32 v11, v8, v2 offset0:192 offset1:224
	v_mul_f32_e32 v2, v16, v4
	v_mul_f32_e32 v10, v33, v5
	ds_write2_b32 v7, v9, v2 offset0:64 offset1:96
	v_mul_f32_e32 v2, v17, v5
	ds_write2_b32 v7, v10, v2 offset0:192 offset1:224
